# static priority 1 for waves 4-7 from kernel entry (restored after attention), no per-segment flips in GEMM phases
# baseline (speedup 1.0000x reference)
; #define LAS __attribute__((address_space(3)))
; __global__ void __launch_bounds__(NWAVES * 64, 2) mk_fwd(Args args) {
;     extern __shared__ __attribute__((aligned(16))) unsigned char lds[];
;     Frame F;
;     F.lds = (LAS unsigned char*)lds;
;     F.tid = threadIdx.x; F.lane = F.tid & 63; F.wave = __builtin_amdgcn_readfirstlane(F.tid >> 6);
;     F.G = gridDim.x; { const int bx = blockIdx.x; F.vcu = (F.G % 8 == 0) ? (bx % 8) * (F.G / 8) + bx / 8 : bx; }
_Z6mk_fwd4Args:
	s_mov_b32 s98, 0
	s_load_dword s94, s[0:1], 0x110
	s_mov_b32 s97, s2
	v_readfirstlane_b32 s2, v0
	s_mov_b32 s77, s97
	s_nop 0
	v_writelane_b32 v254, s2, 0
	s_lshr_b32 s100, s2, 8
	s_cmp_lg_u32 s100, 0
	s_cbranch_scc0 .Lprio_entry_done
	s_setprio 1
.Lprio_entry_done:
	s_add_u32 s2, s0, 0x110
	s_addc_u32 s3, s1, 0
	v_writelane_b32 v254, s2, 1
	s_nop 1
	v_writelane_b32 v254, s3, 2
	s_waitcnt lgkmcnt(0)
	s_and_b32 s2, s94, 7
	s_cmp_lg_u32 s2, 0
	s_cbranch_scc1 .LBB0_2
	s_ashr_i32 s3, s97, 31
	s_lshr_b32 s3, s3, 29
	s_add_i32 s3, s97, s3
	s_and_b32 s4, s3, -8
	s_ashr_i32 s2, s94, 3
	s_sub_i32 s4, s97, s4
	s_mul_i32 s2, s2, s4
	s_ashr_i32 s3, s3, 3
	s_add_i32 s77, s2, s3

; __device__ __forceinline__ void ph_attn(Frame& F) {
;     ...
;         AT_PVMM(vf);
;         if (AT_PRIO) __builtin_amdgcn_s_setprio(0);
;     ...
;         l_run += __shfl_xor(l_run, 32);
;         if (hi == 0) wsf[r32] = 1.0f / l_run;
.LBB0_1011:
	v_mfma_f32_32x32x16_bf16 v[20:35], v[80:83], v[164:167], v[20:35]
	v_mfma_f32_32x32x16_bf16 v[4:19], v[80:83], v[180:183], v[4:19]
	v_mfma_f32_32x32x16_bf16 v[20:35], v[76:79], v[156:159], v[20:35]
	v_mfma_f32_32x32x16_bf16 v[4:19], v[76:79], v[176:179], v[4:19]
	v_mfma_f32_32x32x16_bf16 v[20:35], v[72:75], v[152:155], v[20:35]
	v_mfma_f32_32x32x16_bf16 v[4:19], v[72:75], v[148:151], v[4:19]
	s_setprio 0
	v_readfirstlane_b32 s99, v236
	s_lshr_b32 s99, s99, 8
	s_cmp_lg_u32 s99, 0
	s_cbranch_scc0 .Lprio_attn_done
	s_setprio 1
.Lprio_attn_done:
	v_and_b32_e32 v36, 64, v208
	v_xor_b32_e32 v2, 32, v208
	v_add_u32_e32 v36, 64, v36
	v_cmp_lt_i32_e32 vcc, v2, v36
	s_nop 1
	v_cndmask_b32_e32 v2, v208, v2, vcc
	v_lshlrev_b32_e32 v2, 2, v2
	ds_bpermute_b32 v2, v2, v209
	s_and_saveexec_b64 s[10:11], s[2:3]
	s_cbranch_execz .LBB0_984
	s_waitcnt lgkmcnt(0)
	v_add_f32_e32 v2, v209, v2
	v_div_scale_f32 v36, s[12:13], v2, v2, 1.0
	v_rcp_f32_e32 v37, v36
	v_div_scale_f32 v38, vcc, 1.0, v2, 1.0
	v_fma_f32 v39, -v36, v37, 1.0
	v_fmac_f32_e32 v37, v39, v37
	v_mul_f32_e32 v39, v38, v37
	v_fma_f32 v40, -v36, v39, v38
	v_fmac_f32_e32 v39, v40, v37
	v_fma_f32 v36, -v36, v39, v38
	v_div_fmas_f32 v36, v36, v37, v39
	v_div_fixup_f32 v2, v36, v2, 1.0
	ds_write_b32 v202, v2
	s_branch .LBB0_984
